# cross-attention softmax: half-wave exchanges of the row max and row sum by v_permlane32_swap instead of ds_bpermute LDS round trips
# speedup vs baseline: 1.0100x; 1.0026x over previous
.Lxa_tile:
	s_waitcnt lgkmcnt(7)
	v_mfma_f32_32x32x16_bf16 v[66:81], v[114:117], v[82:85], 0
	ds_read_b128 v[146:149], v181
	s_waitcnt lgkmcnt(7)
	v_mfma_f32_32x32x16_bf16 v[66:81], v[118:121], v[86:89], v[66:81]
	ds_read_b128 v[162:165], v181 offset:1024
	s_waitcnt lgkmcnt(7)
	v_mfma_f32_32x32x16_bf16 v[66:81], v[122:125], v[90:93], v[66:81]
	ds_read_b128 v[150:153], v181 offset:2048
	s_waitcnt lgkmcnt(7)
	v_mfma_f32_32x32x16_bf16 v[66:81], v[126:129], v[94:97], v[66:81]
	ds_read_b128 v[166:169], v181 offset:3072
	s_waitcnt lgkmcnt(7)
	v_mfma_f32_32x32x16_bf16 v[66:81], v[130:133], v[98:101], v[66:81]
	ds_read_b128 v[154:157], v181 offset:4096
	s_waitcnt lgkmcnt(7)
	v_mfma_f32_32x32x16_bf16 v[66:81], v[134:137], v[102:105], v[66:81]
	ds_read_b128 v[170:173], v181 offset:5120
	s_waitcnt lgkmcnt(7)
	v_mfma_f32_32x32x16_bf16 v[66:81], v[138:141], v[106:109], v[66:81]
	ds_read_b128 v[158:161], v181 offset:6144
	s_waitcnt lgkmcnt(7)
	v_mfma_f32_32x32x16_bf16 v[66:81], v[142:145], v[110:113], v[66:81]
	ds_read_b128 v[174:177], v181 offset:7168
	s_nop 11
	v_max3_f32 v212, v66, v67, v68
	v_max3_f32 v213, v69, v70, v71
	v_max3_f32 v220, v72, v73, v74
	v_max3_f32 v221, v75, v76, v77
	v_max3_f32 v238, v78, v79, v80
	v_max3_f32 v212, v212, v213, v220
	v_max3_f32 v221, v221, v238, v81
	v_max_f32_e32 v212, v212, v221
	v_mov_b32_e32 v213, v212
	v_add_u32_e32 v180, 0x2000, v180
	s_nop 0
	v_permlane32_swap_b32_e32 v212, v213
	v_max_f32_e32 v212, v212, v213
	v_mul_f32_e32 v212, 0x3e0293ee, v212
	v_max_f32_e32 v213, v248, v248
	v_max_f32_e32 v220, v213, v212
	v_fma_f32 v66, v66, s67, -v220
	v_fma_f32 v67, v67, s67, -v220
	v_fma_f32 v68, v68, s67, -v220
	v_fma_f32 v69, v69, s67, -v220
	v_fma_f32 v70, v70, s67, -v220
	v_fma_f32 v71, v71, s67, -v220
	v_fma_f32 v72, v72, s67, -v220
	v_fma_f32 v73, v73, s67, -v220
	v_fma_f32 v74, v74, s67, -v220
	v_fma_f32 v75, v75, s67, -v220
	v_fma_f32 v76, v76, s67, -v220
	v_fma_f32 v77, v77, s67, -v220
	v_fma_f32 v78, v78, s67, -v220
	v_fma_f32 v79, v79, s67, -v220
	v_fma_f32 v80, v80, s67, -v220
	v_fma_f32 v81, v81, s67, -v220
	s_waitcnt lgkmcnt(0)
	ds_read_b128 v[114:117], v180
	ds_read_b128 v[118:121], v180 offset:1024
	ds_read_b128 v[122:125], v180 offset:2048
	ds_read_b128 v[126:129], v180 offset:3072
	ds_read_b128 v[130:133], v180 offset:4096
	ds_read_b128 v[134:137], v180 offset:5120
	ds_read_b128 v[138:141], v180 offset:6144
	ds_read_b128 v[142:145], v180 offset:7168
	v_exp_f32_e32 v66, v66
	v_exp_f32_e32 v67, v67
	v_add_f32_e32 v221, 0, v66
	v_exp_f32_e32 v68, v68
	v_add_f32_e32 v221, v67, v221
	v_exp_f32_e32 v69, v69
	v_add_f32_e32 v221, v68, v221
	v_exp_f32_e32 v70, v70
	v_add_f32_e32 v221, v69, v221
	v_exp_f32_e32 v71, v71
	v_add_f32_e32 v221, v70, v221
	v_exp_f32_e32 v72, v72
	v_add_f32_e32 v221, v71, v221
	v_exp_f32_e32 v73, v73
	v_add_f32_e32 v221, v72, v221
	v_exp_f32_e32 v74, v74
	v_add_f32_e32 v221, v73, v221
	v_exp_f32_e32 v75, v75
	v_add_f32_e32 v221, v74, v221
	v_exp_f32_e32 v76, v76
	v_add_f32_e32 v221, v75, v221
	v_exp_f32_e32 v77, v77
	v_add_f32_e32 v221, v76, v221
	v_exp_f32_e32 v78, v78
	v_add_f32_e32 v221, v77, v221
	v_exp_f32_e32 v79, v79
	v_add_f32_e32 v221, v78, v221
	v_exp_f32_e32 v80, v80
	v_add_f32_e32 v221, v79, v221
	v_exp_f32_e32 v81, v81
	v_add_f32_e32 v221, v80, v221
	v_sub_f32_e32 v213, v248, v220
	v_add_f32_e32 v221, v81, v221
	v_exp_f32_e32 v236, v213
	v_mov_b32_e32 v238, v221
	v_mov_b32_e32 v248, v220
	v_cmp_neq_f32_e32 vcc, 1.0, v236
	v_permlane32_swap_b32_e32 v221, v238
	s_cbranch_vccz .Lxa_noresc
	v_pk_mul_f32 v[64:65], v[64:65], v[236:237] op_sel_hi:[1,0]
	v_pk_mul_f32 v[62:63], v[62:63], v[236:237] op_sel_hi:[1,0]
	v_pk_mul_f32 v[60:61], v[60:61], v[236:237] op_sel_hi:[1,0]
	v_pk_mul_f32 v[58:59], v[58:59], v[236:237] op_sel_hi:[1,0]
	v_pk_mul_f32 v[56:57], v[56:57], v[236:237] op_sel_hi:[1,0]
	v_pk_mul_f32 v[54:55], v[54:55], v[236:237] op_sel_hi:[1,0]
	v_pk_mul_f32 v[52:53], v[52:53], v[236:237] op_sel_hi:[1,0]
	v_pk_mul_f32 v[50:51], v[50:51], v[236:237] op_sel_hi:[1,0]
	v_pk_mul_f32 v[48:49], v[48:49], v[236:237] op_sel_hi:[1,0]
	v_pk_mul_f32 v[46:47], v[46:47], v[236:237] op_sel_hi:[1,0]
	v_pk_mul_f32 v[44:45], v[44:45], v[236:237] op_sel_hi:[1,0]
	v_pk_mul_f32 v[42:43], v[42:43], v[236:237] op_sel_hi:[1,0]
	v_pk_mul_f32 v[40:41], v[40:41], v[236:237] op_sel_hi:[1,0]
	v_pk_mul_f32 v[38:39], v[38:39], v[236:237] op_sel_hi:[1,0]
	v_pk_mul_f32 v[36:37], v[36:37], v[236:237] op_sel_hi:[1,0]
	v_pk_mul_f32 v[34:35], v[34:35], v[236:237] op_sel_hi:[1,0]
	v_pk_mul_f32 v[32:33], v[32:33], v[236:237] op_sel_hi:[1,0]
	v_pk_mul_f32 v[30:31], v[30:31], v[236:237] op_sel_hi:[1,0]
	v_pk_mul_f32 v[28:29], v[28:29], v[236:237] op_sel_hi:[1,0]
	v_pk_mul_f32 v[26:27], v[26:27], v[236:237] op_sel_hi:[1,0]
	v_pk_mul_f32 v[24:25], v[24:25], v[236:237] op_sel_hi:[1,0]
	v_pk_mul_f32 v[22:23], v[22:23], v[236:237] op_sel_hi:[1,0]
	v_pk_mul_f32 v[20:21], v[20:21], v[236:237] op_sel_hi:[1,0]
	v_pk_mul_f32 v[18:19], v[18:19], v[236:237] op_sel_hi:[1,0]
	v_pk_mul_f32 v[16:17], v[16:17], v[236:237] op_sel_hi:[1,0]
	v_pk_mul_f32 v[14:15], v[14:15], v[236:237] op_sel_hi:[1,0]
	v_pk_mul_f32 v[12:13], v[12:13], v[236:237] op_sel_hi:[1,0]
	v_pk_mul_f32 v[10:11], v[10:11], v[236:237] op_sel_hi:[1,0]
	v_pk_mul_f32 v[8:9], v[8:9], v[236:237] op_sel_hi:[1,0]
	v_pk_mul_f32 v[6:7], v[6:7], v[236:237] op_sel_hi:[1,0]
	v_pk_mul_f32 v[4:5], v[4:5], v[236:237] op_sel_hi:[1,0]
	v_pk_mul_f32 v[2:3], v[2:3], v[236:237] op_sel_hi:[1,0]
.Lxa_noresc:
	v_add_f32_e32 v221, v221, v238
	v_fmac_f32_e32 v221, v231, v236
	s_nop 0
	v_mov_b32_e32 v231, v221
	v_cvt_pk_bf16_f32 v66, v66, v67
	v_cvt_pk_bf16_f32 v67, v68, v69
	v_cvt_pk_bf16_f32 v68, v70, v71
	v_cvt_pk_bf16_f32 v69, v72, v73
	v_cvt_pk_bf16_f32 v70, v74, v75
	v_cvt_pk_bf16_f32 v71, v76, v77
	v_cvt_pk_bf16_f32 v72, v78, v79
	v_cvt_pk_bf16_f32 v73, v80, v81
	s_nop 1
	v_mfma_f32_32x32x16_bf16 v[50:65], v[146:149], v[66:69], v[50:65]
	v_mfma_f32_32x32x16_bf16 v[34:49], v[150:153], v[66:69], v[34:49]
	v_mfma_f32_32x32x16_bf16 v[18:33], v[154:157], v[66:69], v[18:33]
	v_mfma_f32_32x32x16_bf16 v[2:17], v[158:161], v[66:69], v[2:17]
	v_mfma_f32_32x32x16_bf16 v[50:65], v[162:165], v[70:73], v[50:65]
	v_mfma_f32_32x32x16_bf16 v[34:49], v[166:169], v[70:73], v[34:49]
	v_mfma_f32_32x32x16_bf16 v[18:33], v[170:173], v[70:73], v[18:33]
	v_mfma_f32_32x32x16_bf16 v[2:17], v[174:177], v[70:73], v[2:17]
	v_add_u32_e32 v181, 0x2000, v181
	s_add_i32 s11, s11, 1
	s_cmp_lt_u32 s11, 8
	s_cbranch_scc1 .Lxa_tile
	s_waitcnt lgkmcnt(0)
	s_nop 15
	s_branch .LBB0_1510
